# sample-chain step: the two 8-lane sums by three v_add_f32_dpp each (quad_perm xor1, xor2, row_half_mirror) instead of three dependent ds_bpermute round trips
# speedup vs baseline: 1.0090x; 1.0019x over previous
.LBB0_1190:
	s_or_b64 exec, exec, s[14:15]
	s_ashr_i32 s11, s10, 31
	s_lshl_b64 s[8:9], s[10:11], 12
	s_waitcnt lgkmcnt(3)
	v_lshl_add_u64 v[22:23], s[8:9], 0, v[2:3]
	v_lshlrev_b64 v[62:63], 2, v[22:23]
	v_lshl_add_u64 v[26:27], v[6:7], 0, v[62:63]
	s_waitcnt lgkmcnt(0)
	s_barrier
	ds_read_b128 v[30:33], v11
	ds_read_b128 v[34:37], v11 offset:16
	s_waitcnt vmcnt(1) lgkmcnt(1)
	v_pk_mul_f32 v[30:31], v[200:201], v[30:31]
	s_nop 0
	v_add_f32_e32 v4, 0, v30
	v_pk_mul_f32 v[32:33], v[202:203], v[32:33]
	v_add_f32_e32 v4, v4, v31
	v_add_f32_e32 v4, v4, v32
	s_waitcnt vmcnt(0) lgkmcnt(0)
	v_pk_mul_f32 v[34:35], v[204:205], v[34:35]
	v_add_f32_e32 v4, v4, v33
	v_add_f32_e32 v4, v4, v34
	v_pk_mul_f32 v[36:37], v[206:207], v[36:37]
	v_add_f32_e32 v4, v4, v35
	v_add_f32_e32 v4, v4, v36
	v_add_f32_e32 v30, v4, v37
	s_nop 0
	ds_read_b32 v4, v15 offset:1280
	s_waitcnt lgkmcnt(1)
	v_add_f32_dpp v46, v30, v30 quad_perm:[1,0,3,2] row_mask:0xf bank_mask:0xf bound_ctrl:1
	s_nop 0
	ds_read_b128 v[30:33], v11 offset:1024
	ds_read_b128 v[34:37], v11 offset:1040
	ds_read_b128 v[38:41], v11 offset:256
	ds_read_b128 v[42:45], v11 offset:272
	s_waitcnt lgkmcnt(4)
	v_add_f32_dpp v64, v46, v46 quad_perm:[2,3,0,1] row_mask:0xf bank_mask:0xf bound_ctrl:1
	s_nop 0
	ds_read_b128 v[46:49], v11 offset:512
	ds_read_b128 v[50:53], v11 offset:528
	ds_read_b128 v[54:57], v11 offset:768
	ds_read_b128 v[58:61], v11 offset:784
	s_waitcnt lgkmcnt(4)
	v_add_f32_dpp v64, v64, v64 row_half_mirror row_mask:0xf bank_mask:0xf bound_ctrl:1
	s_waitcnt lgkmcnt(3)
	v_pk_mul_f32 v[46:47], v[64:65], v[46:47] op_sel_hi:[0,1]
	v_pk_mul_f32 v[48:49], v[64:65], v[48:49] op_sel_hi:[0,1]
	v_pk_fma_f32 v[22:23], v[200:201], v[38:39], v[46:47]
	v_pk_fma_f32 v[38:39], v[202:203], v[40:41], v[48:49]
	s_waitcnt lgkmcnt(1)
	v_pk_fma_f32 v[24:25], v[4:5], v[54:55], v[22:23] op_sel_hi:[0,1,1]
	v_pk_mul_f32 v[50:51], v[64:65], v[50:51] op_sel_hi:[0,1]
	v_fma_f32 v22, v30, v24, 0
	v_pk_fma_f32 v[40:41], v[204:205], v[42:43], v[50:51]
	v_pk_fma_f32 v[26:27], v[4:5], v[56:57], v[38:39] op_sel_hi:[0,1,1]
	v_fmac_f32_e32 v22, v31, v25
	v_pk_mul_f32 v[52:53], v[64:65], v[52:53] op_sel_hi:[0,1]
	v_fmac_f32_e32 v22, v32, v26
	v_pk_fma_f32 v[42:43], v[206:207], v[44:45], v[52:53]
	s_waitcnt lgkmcnt(0)
	v_pk_fma_f32 v[28:29], v[4:5], v[58:59], v[40:41] op_sel_hi:[0,1,1]
	v_fmac_f32_e32 v22, v33, v27
	v_fmac_f32_e32 v22, v34, v28
	v_fmac_f32_e32 v22, v35, v29
	v_pk_fma_f32 v[30:31], v[4:5], v[60:61], v[42:43] op_sel_hi:[0,1,1]
	v_fmac_f32_e32 v22, v36, v30
	v_fmac_f32_e32 v22, v37, v31
	s_nop 0
	v_lshl_add_u64 v[32:33], v[8:9], 0, v[62:63]
	global_store_dwordx4 v[32:33], v[24:27], off
	global_store_dwordx4 v[32:33], v[28:31], off offset:16
	s_waitcnt lgkmcnt(0)
	v_add_f32_dpp v4, v22, v22 quad_perm:[1,0,3,2] row_mask:0xf bank_mask:0xf bound_ctrl:1
	s_nop 0
	s_waitcnt lgkmcnt(0)
	s_nop 1
	v_add_f32_dpp v4, v4, v4 quad_perm:[2,3,0,1] row_mask:0xf bank_mask:0xf bound_ctrl:1
	s_nop 1
	v_add_f32_dpp v4, v4, v4 row_half_mirror row_mask:0xf bank_mask:0xf bound_ctrl:1
	s_and_saveexec_b64 s[8:9], s[4:5]
	s_cbranch_execz .LBB0_1186
	s_mul_hi_i32 s11, s12, 0x880
	s_mulk_i32 s12, 0x880
	s_add_u32 s12, s88, s12
	s_addc_u32 s11, s89, s11
	s_lshl_b32 s13, s17, 7
	s_waitcnt lgkmcnt(0)
	s_nop 0
	s_add_u32 s12, s12, s13
	v_bfe_u32 v22, v4, 16, 1
	s_addc_u32 s13, s11, 0
	v_add3_u32 v4, v4, v22, s16
	v_lshl_add_u64 v[22:23], v[0:1], 1, s[12:13]
	global_store_short_d16_hi v[22:23], v4, off
	s_branch .LBB0_1186
